# IN phase: 128x128 rotary-key tiles reassigned to the 50 single-big-tile WGs (2 rounds on 16 of them) instead of WGs 190-255
# speedup vs baseline: 1.0089x; 1.0089x over previous
.LBB0_552:
	v_xad_u32 v50, v162, -1, s58
	s_movk_i32 s0, 0x64
	v_cmp_gt_i32_e32 vcc, s0, v50
	s_and_saveexec_b64 s[42:43], vcc
	s_movk_i32 s4, 0x90
	s_mov_b64 s[8:9], 0x917d880
	s_cbranch_execz .LBB0_571
	v_lshlrev_b32_e32 v0, 7, v163
	v_readlane_b32 s0, v254, 53
	s_mov_b64 s[44:45], 0
	s_nop 0
	v_sub_u32_e32 v51, s0, v0
	s_branch .LBB0_556

.LBB0_555:
	s_or_b64 exec, exec, s[2:3]
	v_add_u32_e32 v50, 0x64, v50
	s_movk_i32 s0, 0x83
	v_cmp_lt_i32_e32 vcc, s0, v50
	s_or_b64 s[44:45], vcc, s[44:45]
	s_nop 0
	v_add_u32_e32 v51, 0x3200, v51
	s_andn2_b64 exec, exec, s[44:45]
	s_cbranch_execz .LBB0_571
